# v26 + dilated (phase A) tile loop: activity test and the eight K-fragment reads issued before the stream loader runs
# speedup vs baseline: 1.0275x; 1.0027x over previous
.LBB0_358:
	s_cmp_lt_u32 s75, s74
	s_cselect_b32 s100, 1, 0
	s_cmp_ge_u32 s77, s95
	s_cselect_b32 s101, 1, 0
	s_and_b32 s100, s100, s101
	s_cmp_le_u32 s77, s3
	s_cselect_b32 s101, 1, 0
	s_and_b32 s100, s100, s101
	s_xor_b32 s0, s77, s95
	s_cmp_lt_u32 s0, 4
	s_cselect_b32 s101, 1, 0
	s_and_b32 s0, s77, 3
	s_sub_i32 s0, s0, s84
	s_add_i32 s0, s0, 2
	s_cmp_lt_u32 s0, 5
	s_cselect_b32 s0, 1, 0
	s_and_b32 s101, s101, s0
	s_and_b64 s[0:1], s[14:15], exec
	s_cselect_b32 s100, s100, s101
	s_cmp_lg_u32 s100, 0
	s_cbranch_scc0 .Ldilp_nopre
	s_lshl_b32 s0, s59, 14
	v_add_u32_e32 v250, s0, v248
	v_xor_b32_e32 v0, 32, v250
	v_xor_b32_e32 v95, 64, v250
	ds_read_b128 v[66:69], v250
	ds_read_b128 v[216:219], v0
	v_xor_b32_e32 v0, 0x60, v250
	ds_read_b128 v[220:223], v95
	v_xor_b32_e32 v95, 0x80, v250
	ds_read_b128 v[224:227], v0
	v_xor_b32_e32 v0, 0xa0, v250
	ds_read_b128 v[228:231], v95
	v_xor_b32_e32 v95, 0xc0, v250
	ds_read_b128 v[232:235], v0
	v_xor_b32_e32 v0, 0xe0, v250
	ds_read_b128 v[236:239], v95
	ds_read_b128 v[240:243], v0

.LBB0_370:
	s_lshl_b32 s16, s65, 14
	v_mov_b32_e32 v95, v1
	s_add_i32 s16, s85, s16
	v_lshl_add_u64 v[246:247], s[0:1], 0, v[94:95]
	s_mov_b32 m0, s16
	v_lshl_add_u64 v[246:247], v[246:247], 0, s[98:99]
	global_load_lds_dwordx4 v94, s[0:1]
	s_add_i32 m0, s16, 0x2000
	s_nop 0
	global_load_lds_dwordx4 v[246:247], off
	s_cbranch_execz .LBB0_374
	s_branch .LBB0_375

.LBB0_391:
	s_xor_b64 s[80:81], s[80:81], -1
	s_cmp_lg_u32 s100, 0
	s_cbranch_scc0 .LBB0_408
	s_lshl_b32 s0, s59, 14
	s_add_i32 s28, s0, 0x2000
	v_add_u32_e32 v251, s0, v249
	s_waitcnt lgkmcnt(7)
	v_mfma_f32_32x32x16_bf16 v[66:81], v[66:69], v[82:85], 0
	s_and_b32 s0, s77, 3
	s_sub_i32 s16, s0, s84
	v_readlane_b32 s0, v254, 31
	s_add_i32 s17, s0, s77
	s_and_b64 s[0:1], s[10:11], exec
	s_cselect_b32 s29, s16, s17
	s_cmp_lt_i32 s29, 2
	s_waitcnt lgkmcnt(6)
	v_mfma_f32_32x32x16_bf16 v[66:81], v[216:219], v[86:89], v[66:81]
	s_waitcnt lgkmcnt(5)
	v_mfma_f32_32x32x16_bf16 v[66:81], v[220:223], v[90:93], v[66:81]
	s_waitcnt lgkmcnt(4)
	v_mfma_f32_32x32x16_bf16 v[66:81], v[224:227], v[128:131], v[66:81]
	s_waitcnt lgkmcnt(3)
	v_mfma_f32_32x32x16_bf16 v[66:81], v[228:231], v[132:135], v[66:81]
	s_waitcnt lgkmcnt(2)
	v_mfma_f32_32x32x16_bf16 v[66:81], v[232:235], v[136:139], v[66:81]
	s_waitcnt lgkmcnt(1)
	v_mfma_f32_32x32x16_bf16 v[66:81], v[236:239], v[140:143], v[66:81]
	s_waitcnt lgkmcnt(0)
	v_mfma_f32_32x32x16_bf16 v[66:81], v[240:243], v[144:147], v[66:81]
	v_xor_b32_e32 v0, 0x820, v251
	v_xor_b32_e32 v95, 64, v251
	v_xor_b32_e32 v250, 0x860, v251
	v_xor_b32_e32 v244, 0x80, v251
	v_xor_b32_e32 v245, 0x8a0, v251
	v_xor_b32_e32 v246, 0xc0, v251
	v_xor_b32_e32 v247, 0x8e0, v251
	ds_read_b64_tr_b16 v[216:217], v251
	ds_read_b64_tr_b16 v[218:219], v0
	ds_read_b64_tr_b16 v[220:221], v95
	ds_read_b64_tr_b16 v[222:223], v250
	ds_read_b64_tr_b16 v[224:225], v244
	ds_read_b64_tr_b16 v[226:227], v245
	ds_read_b64_tr_b16 v[200:201], v246
	ds_read_b64_tr_b16 v[202:203], v247
	ds_read_b64_tr_b16 v[228:229], v251 offset:4096
	ds_read_b64_tr_b16 v[230:231], v0 offset:4096
	ds_read_b64_tr_b16 v[232:233], v95 offset:4096
	ds_read_b64_tr_b16 v[234:235], v250 offset:4096
	ds_read_b64_tr_b16 v[236:237], v244 offset:4096
	ds_read_b64_tr_b16 v[238:239], v245 offset:4096
	ds_read_b64_tr_b16 v[240:241], v246 offset:4096
	ds_read_b64_tr_b16 v[242:243], v247 offset:4096
	s_cbranch_scc1 .LBB0_401
	s_cmp_eq_u32 s29, 2
	s_cselect_b64 s[0:1], -1, 0
	s_cbranch_execz .LBB0_402
	s_branch .LBB0_403

	.amdhsa_kernel _Z10fwd_kernel6Params
		.amdhsa_group_segment_fixed_size 0
		.amdhsa_private_segment_fixed_size 0
		.amdhsa_kernarg_size 344
		.amdhsa_user_sgpr_count 2
		.amdhsa_user_sgpr_dispatch_ptr 0
		.amdhsa_user_sgpr_queue_ptr 0
		.amdhsa_user_sgpr_kernarg_segment_ptr 1
		.amdhsa_user_sgpr_dispatch_id 0
		.amdhsa_user_sgpr_kernarg_preload_length 0
		.amdhsa_user_sgpr_kernarg_preload_offset 0
		.amdhsa_user_sgpr_private_segment_size 0
		.amdhsa_uses_dynamic_stack 0
		.amdhsa_enable_private_segment 0
		.amdhsa_system_sgpr_workgroup_id_x 1
		.amdhsa_system_sgpr_workgroup_id_y 0
		.amdhsa_system_sgpr_workgroup_id_z 0
		.amdhsa_system_sgpr_workgroup_info 0
		.amdhsa_system_vgpr_workitem_id 2
		.amdhsa_next_free_vgpr 256
		.amdhsa_next_free_sgpr 102
		.amdhsa_accum_offset 256
		.amdhsa_reserve_vcc 1
		.amdhsa_float_round_mode_32 0
		.amdhsa_float_round_mode_16_64 0
		.amdhsa_float_denorm_mode_32 3
		.amdhsa_float_denorm_mode_16_64 3
		.amdhsa_dx10_clamp 1
		.amdhsa_ieee_mode 1
		.amdhsa_fp16_overflow 0
		.amdhsa_tg_split 0
		.amdhsa_exception_fp_ieee_invalid_op 0
		.amdhsa_exception_fp_denorm_src 0
		.amdhsa_exception_fp_ieee_div_zero 0
		.amdhsa_exception_fp_ieee_overflow 0
		.amdhsa_exception_fp_ieee_underflow 0
		.amdhsa_exception_fp_ieee_inexact 0
		.amdhsa_exception_int_div_zero 0
	.end_amdhsa_kernel

amdhsa.kernels:
  - .agpr_count:     0
    .args:
      - .offset:         0
        .size:           88
        .value_kind:     by_value
      - .offset:         88
        .size:           4
        .value_kind:     hidden_block_count_x
      - .offset:         92
        .size:           4
        .value_kind:     hidden_block_count_y
      - .offset:         96
        .size:           4
        .value_kind:     hidden_block_count_z
      - .offset:         100
        .size:           2
        .value_kind:     hidden_group_size_x
      - .offset:         102
        .size:           2
        .value_kind:     hidden_group_size_y
      - .offset:         104
        .size:           2
        .value_kind:     hidden_group_size_z
      - .offset:         106
        .size:           2
        .value_kind:     hidden_remainder_x
      - .offset:         108
        .size:           2
        .value_kind:     hidden_remainder_y
      - .offset:         110
        .size:           2
        .value_kind:     hidden_remainder_z
      - .offset:         128
        .size:           8
        .value_kind:     hidden_global_offset_x
      - .offset:         136
        .size:           8
        .value_kind:     hidden_global_offset_y
      - .offset:         144
        .size:           8
        .value_kind:     hidden_global_offset_z
      - .offset:         152
        .size:           2
        .value_kind:     hidden_grid_dims
      - .offset:         176
        .size:           8
        .value_kind:     hidden_multigrid_sync_arg
      - .offset:         208
        .size:           4
        .value_kind:     hidden_dynamic_lds_size
    .group_segment_fixed_size: 0
    .kernarg_segment_align: 8
    .kernarg_segment_size: 344
    .language:       OpenCL C
    .language_version:
      - 2
      - 0
    .max_flat_workgroup_size: 512
    .name:           _Z10fwd_kernel6Params
    .private_segment_fixed_size: 0
    .sgpr_count:     108
    .sgpr_spill_count: 206
    .symbol:         _Z10fwd_kernel6Params.kd
    .uniform_work_group_size: 1
    .uses_dynamic_stack: false
    .vgpr_count:     256
    .vgpr_spill_count: 0
    .wavefront_size: 64
